# XCD-local seams P4->P5->P6' (per-XCD barriers 4,5 when each class sits on one XCD; SchedFinal remapped) + 3us/XCD start stagger; P4/P6' epilogues de-serialised
# speedup vs baseline: 1.0133x; 1.0049x over previous
.LBB0_20:
	s_or_b64 exec, exec, s[6:7]
	s_load_dwordx16 s[4:19], s[0:1], 0x0
	s_and_b32 s0, s20, 15
	s_barrier
	v_writelane_b32 v254, s0, 0
	s_waitcnt lgkmcnt(0)
	s_and_saveexec_b64 s[0:1], vcc
	s_cbranch_execz .LBB0_23
	s_mov_b64 s[34:35], exec
	v_mbcnt_lo_u32_b32 v0, s34, 0
	v_mbcnt_hi_u32_b32 v0, s35, v0
	v_cmp_eq_u32_e32 vcc, 0, v0
	s_and_b64 s[20:21], exec, vcc
	s_mov_b64 exec, s[20:21]
	s_cbranch_execz .LBB0_23
	v_readlane_b32 s20, v254, 0
	s_lshl_b32 s20, s20, 8
	s_bcnt1_i32_b64 s21, s[34:35]
	v_mov_b32_e32 v0, s20
	v_mov_b32_e32 v1, s21
	global_atomic_add v0, v1, s[36:37] offset:1024
	s_and_b32 s21, s2, 7
	s_lshl_b32 s21, s21, 2
	v_readlane_b32 s20, v254, 0
	s_nop 3
	s_lshl_b32 s20, 1, s20
	v_mov_b32_e32 v0, s21
	v_mov_b32_e32 v1, s20
	global_atomic_or v0, v1, s[36:37] offset:32

.LBB0_392:
	s_or_b64 exec, exec, s[0:1]
	v_mov_b32_e32 v0, 0
	s_add_u32 s98, s66, 0x40000
	s_addc_u32 s99, s67, 0
	s_nop 0
	global_load_dwordx4 v[4:7], v0, s[98:99] offset:32 sc1
	global_load_dwordx4 v[8:11], v0, s[98:99] offset:48 sc1
	s_mov_b32 s100, 1
	s_waitcnt vmcnt(0)
	v_readfirstlane_b32 s101, v4
	s_bcnt1_i32_b32 s101, s101
	s_cmp_eq_u32 s101, 1
	s_cselect_b32 s100, s100, 0
	v_readfirstlane_b32 s101, v5
	s_bcnt1_i32_b32 s101, s101
	s_cmp_eq_u32 s101, 1
	s_cselect_b32 s100, s100, 0
	v_readfirstlane_b32 s101, v6
	s_bcnt1_i32_b32 s101, s101
	s_cmp_eq_u32 s101, 1
	s_cselect_b32 s100, s100, 0
	v_readfirstlane_b32 s101, v7
	s_bcnt1_i32_b32 s101, s101
	s_cmp_eq_u32 s101, 1
	s_cselect_b32 s100, s100, 0
	v_readfirstlane_b32 s101, v8
	s_bcnt1_i32_b32 s101, s101
	s_cmp_eq_u32 s101, 1
	s_cselect_b32 s100, s100, 0
	v_readfirstlane_b32 s101, v9
	s_bcnt1_i32_b32 s101, s101
	s_cmp_eq_u32 s101, 1
	s_cselect_b32 s100, s100, 0
	v_readfirstlane_b32 s101, v10
	s_bcnt1_i32_b32 s101, s101
	s_cmp_eq_u32 s101, 1
	s_cselect_b32 s100, s100, 0
	v_readfirstlane_b32 s101, v11
	s_bcnt1_i32_b32 s101, s101
	s_cmp_eq_u32 s101, 1
	s_cselect_b32 s100, s100, 0
	v_writelane_b32 v255, s100, 0
	s_cmp_eq_u32 s100, 0
	s_cbranch_scc1 .Lxl_stag_done
	v_readlane_b32 s101, v254, 0
	s_nop 3
	s_cmp_eq_u32 s101, 0
	s_cbranch_scc1 .Lxl_stag_done
.Lxl_stag_loop:
	s_sleep 96
	s_add_i32 s101, s101, -1
	s_cmp_lg_u32 s101, 0
	s_cbranch_scc1 .Lxl_stag_loop
.Lxl_stag_done:
	s_cmpk_lt_i32 s2, 0x200
	s_cselect_b64 s[0:1], -1, 0
	s_cmpk_gt_i32 s2, 0x1ff
	s_waitcnt lgkmcnt(0)
	s_barrier
	v_mbcnt_lo_u32_b32 v8, -1, 0
	v_mbcnt_hi_u32_b32 v8, -1, v8
	s_cbranch_scc1 .LBB0_398
	s_ashr_i32 s4, s2, 31
	s_lshr_b32 s4, s4, 29
	s_add_i32 s8, s2, s4
	s_and_b32 s4, s8, -8
	s_sub_i32 s9, s2, s4
	s_cmp_gt_i32 s9, -1
	s_cbranch_scc0 .LBB0_395
	s_lshl_b32 s10, s9, 6
	s_cbranch_execz .LBB0_396
	s_branch .LBB0_397

.LBB0_436:
	v_mbcnt_lo_u32_b32 v0, -1, 0
	v_mbcnt_hi_u32_b32 v0, -1, v0
	s_waitcnt vmcnt(0)
	v_readlane_b32 s4, v254, 6
	v_sub_u32_e32 v0, 0, v0
	s_waitcnt lgkmcnt(0)
	v_cmp_eq_u32_e32 vcc, s4, v0
	s_barrier
	s_and_saveexec_b64 s[4:5], vcc
	s_cbranch_execz .LBB0_488
	v_readlane_b32 s6, v255, 0
	s_nop 3
	s_cmp_eq_u32 s6, 0
	s_cbranch_scc1 .Lxl_b4_global
	v_mov_b32_e32 v0, 0x20400
	ds_read_b32 v2, v0
	v_readlane_b32 s6, v254, 0
	s_nop 3
	s_lshl_b32 s6, s6, 8
	s_add_u32 s6, s6, 0x40000
	s_add_u32 s6, s66, s6
	s_addc_u32 s7, s67, 0
	v_mov_b32_e32 v3, 0x1400
	v_mov_b32_e32 v4, 1
	s_waitcnt lgkmcnt(0)
	v_readfirstlane_b32 s8, v2
	global_atomic_add v5, v3, v4, s[6:7] sc0
	s_mul_i32 s10, s8, 4
	s_waitcnt vmcnt(0)
	v_readfirstlane_b32 s9, v5
	s_add_i32 s9, s9, 1
	v_mov_b32_e32 v3, 0x2400
	s_cmp_eq_u32 s9, s10
	s_cbranch_scc0 .Lxl_b4_wait
	global_atomic_add v3, v4, s[6:7]
	s_branch .Lxl_b4_acq
.Lxl_b4_wait:
	s_mov_b32 s11, 0
.Lxl_b4_spin:
	s_sleep 1
	global_load_dword v5, v3, s[6:7] sc1
	s_waitcnt vmcnt(0)
	v_readfirstlane_b32 s9, v5
	s_cmp_lg_u32 s9, 3
	s_cbranch_scc1 .Lxl_b4_acq
	s_add_i32 s11, s11, 1
	s_cmp_lt_u32 s11, 2000
	s_cbranch_scc1 .Lxl_b4_spin
.Lxl_b4_acq:
	s_waitcnt vmcnt(0)
	buffer_inv sc1
	s_waitcnt vmcnt(0)
	s_branch .LBB0_488
.Lxl_b4_global:
	s_add_i32 s6, 0, 0x20400
	v_mov_b32_e32 v0, s6
	s_waitcnt vmcnt(0) expcnt(0) lgkmcnt(0)
	ds_read_b32 v2, v0
	s_add_i32 s6, 0, 0x20404
	v_mov_b32_e32 v0, s6
	ds_read_b32 v0, v0
	s_waitcnt lgkmcnt(1)
	v_cmp_ne_u32_e32 vcc, 0, v2
	s_cbranch_vccnz .LBB0_452
	s_add_u32 s6, s66, 0x40200
	s_addc_u32 s7, s67, 0
	s_add_u32 s8, s66, 0x40400
	s_addc_u32 s9, s67, 0
	s_add_u32 s14, s66, 0x40500
	s_addc_u32 s15, s67, 0
	s_add_u32 s16, s66, 0x40600
	s_addc_u32 s17, s67, 0
	s_add_u32 s20, s66, 0x40700
	s_addc_u32 s21, s67, 0
	s_add_u32 s22, s66, 0x40800
	s_addc_u32 s23, s67, 0
	s_add_u32 s24, s66, 0x40900
	s_addc_u32 s25, s67, 0
	s_add_u32 s42, s66, 0x40a00
	s_addc_u32 s43, s67, 0
	s_add_u32 s44, s66, 0x40b00
	s_addc_u32 s45, s67, 0
	s_add_u32 s46, s66, 0x40c00
	s_addc_u32 s47, s67, 0
	s_add_u32 s48, s66, 0x40d00
	s_addc_u32 s49, s67, 0
	s_add_u32 s50, s66, 0x40e00
	s_addc_u32 s51, s67, 0
	s_add_u32 s52, s66, 0x40f00
	s_addc_u32 s53, s67, 0
	s_add_u32 s54, s66, 0x41000
	s_addc_u32 s55, s67, 0
	s_add_u32 s56, s66, 0x41100
	s_addc_u32 s57, s67, 0
	s_add_u32 s58, s66, 0x41200
	s_addc_u32 s59, s67, 0
	s_add_u32 s60, s66, 0x41300
	s_addc_u32 s61, s67, 0
	s_mov_b32 s76, 1
	v_mov_b32_e32 v16, 0
	s_branch .LBB0_440

.LBB0_514:
	v_mbcnt_lo_u32_b32 v0, -1, 0
	v_mbcnt_hi_u32_b32 v0, -1, v0
	s_waitcnt vmcnt(0)
	v_readlane_b32 s4, v254, 6
	v_sub_u32_e32 v0, 0, v0
	s_waitcnt vmcnt(0)
	v_cmp_eq_u32_e32 vcc, s4, v0
	s_barrier
	s_and_saveexec_b64 s[4:5], vcc
	s_cbranch_execz .LBB0_566
	v_readlane_b32 s6, v255, 0
	s_nop 3
	s_cmp_eq_u32 s6, 0
	s_cbranch_scc1 .Lxl_b5_global
	v_mov_b32_e32 v0, 0x20400
	ds_read_b32 v2, v0
	v_readlane_b32 s6, v254, 0
	s_nop 3
	s_lshl_b32 s6, s6, 8
	s_add_u32 s6, s6, 0x40000
	s_add_u32 s6, s66, s6
	s_addc_u32 s7, s67, 0
	v_mov_b32_e32 v3, 0x1400
	v_mov_b32_e32 v4, 1
	s_waitcnt lgkmcnt(0)
	v_readfirstlane_b32 s8, v2
	global_atomic_add v5, v3, v4, s[6:7] sc0
	s_mul_i32 s10, s8, 5
	s_waitcnt vmcnt(0)
	v_readfirstlane_b32 s9, v5
	s_add_i32 s9, s9, 1
	v_mov_b32_e32 v3, 0x2400
	s_cmp_eq_u32 s9, s10
	s_cbranch_scc0 .Lxl_b5_wait
	global_atomic_add v3, v4, s[6:7]
	s_branch .Lxl_b5_acq

.Lxl_b5_spin:
	s_sleep 1
	global_load_dword v5, v3, s[6:7] sc1
	s_waitcnt vmcnt(0)
	v_readfirstlane_b32 s9, v5
	s_cmp_lg_u32 s9, 4
	s_cbranch_scc1 .Lxl_b5_acq
	s_add_i32 s11, s11, 1
	s_cmp_lt_u32 s11, 2000
	s_cbranch_scc1 .Lxl_b5_spin

.Lxl_b5_global:
	s_add_i32 s6, 0, 0x20400
	v_mov_b32_e32 v0, s6
	s_waitcnt vmcnt(0) expcnt(0) lgkmcnt(0)
	ds_read_b32 v2, v0
	s_add_i32 s6, 0, 0x20404
	v_mov_b32_e32 v0, s6
	ds_read_b32 v0, v0
	s_waitcnt lgkmcnt(1)
	v_cmp_ne_u32_e32 vcc, 0, v2
	s_cbranch_vccnz .LBB0_530
	s_add_u32 s6, s66, 0x40200
	s_addc_u32 s7, s67, 0
	s_add_u32 s8, s66, 0x40400
	s_addc_u32 s9, s67, 0
	s_add_u32 s14, s66, 0x40500
	s_addc_u32 s15, s67, 0
	s_add_u32 s16, s66, 0x40600
	s_addc_u32 s17, s67, 0
	s_add_u32 s20, s66, 0x40700
	s_addc_u32 s21, s67, 0
	s_add_u32 s22, s66, 0x40800
	s_addc_u32 s23, s67, 0
	s_add_u32 s24, s66, 0x40900
	s_addc_u32 s25, s67, 0
	s_add_u32 s42, s66, 0x40a00
	s_addc_u32 s43, s67, 0
	s_add_u32 s44, s66, 0x40b00
	s_addc_u32 s45, s67, 0
	s_add_u32 s46, s66, 0x40c00
	s_addc_u32 s47, s67, 0
	s_add_u32 s48, s66, 0x40d00
	s_addc_u32 s49, s67, 0
	s_add_u32 s50, s66, 0x40e00
	s_addc_u32 s51, s67, 0
	s_add_u32 s52, s66, 0x40f00
	s_addc_u32 s53, s67, 0
	s_add_u32 s54, s66, 0x41000
	s_addc_u32 s55, s67, 0
	s_add_u32 s56, s66, 0x41100
	s_addc_u32 s57, s67, 0
	s_add_u32 s58, s66, 0x41200
	s_addc_u32 s59, s67, 0
	s_add_u32 s60, s66, 0x41300
	s_addc_u32 s61, s67, 0
	s_mov_b32 s39, 1
	v_mov_b32_e32 v16, 0
	s_branch .LBB0_518

.LBB0_667:
	s_and_b64 vcc, exec, s[4:5]
	s_cbranch_vccz .LBB0_703
	v_mbcnt_lo_u32_b32 v7, -1, 0
	v_mbcnt_hi_u32_b32 v7, -1, v7
	v_readlane_b32 s3, v254, 17
	v_lshl_add_u32 v0, v7, 4, s40
	v_ashrrev_i32_e32 v1, 31, v0
	v_lshrrev_b32_e32 v1, 22, v1
	v_add_u32_e32 v1, v0, v1
	v_ashrrev_i32_e32 v4, 10, v1
	v_mul_i32_i24_e32 v1, 0x400, v4
	v_sub_u32_e32 v1, v0, v1
	v_lshrrev_b32_e32 v2, 4, v1
	v_bitop3_b32 v1, v2, v1, 32 bitop3:0x6c
	v_ashrrev_i32_e32 v3, 31, v1
	v_lshrrev_b32_e32 v3, 26, v3
	v_add_u32_e32 v3, v1, v3
	v_lshlrev_b32_e32 v2, 3, v4
	v_ashrrev_i32_e32 v5, 6, v3
	v_and_b32_e32 v3, 0xc0, v3
	v_and_b32_e32 v2, -16, v2
	v_sub_u32_e32 v1, v1, v3
	v_mov_b32_e32 v3, 1
	v_add_u32_e32 v2, v5, v2
	v_lshlrev_b32_e32 v6, 5, v4
	v_ashrrev_i16_sdwa v1, v3, sext(v1) dst_sel:DWORD dst_unused:UNUSED_PAD src0_sel:DWORD src1_sel:BYTE_0
	s_mov_b32 m0, s3
	v_and_b32_e32 v8, 32, v6
	v_bfe_i32 v6, v1, 0, 16
	v_lshlrev_b32_e32 v1, 1, v2
	v_lshrrev_b32_e32 v9, 2, v2
	v_and_b32_e32 v10, 3, v5
	s_mov_b32 s3, 0x3ffe0
	v_and_b32_e32 v1, 24, v1
	v_and_b32_e32 v9, 4, v9
	v_and_or_b32 v10, v2, s3, v10
	v_or3_b32 v1, v10, v9, v1
	v_add_lshl_u32 v8, v8, v6, 1
	v_add_u32_e32 v0, 0x2000, v0
	v_lshl_add_u32 v138, v1, 14, v8
	v_ashrrev_i32_e32 v1, 31, v0
	v_lshrrev_b32_e32 v1, 22, v1
	v_add_u32_e32 v1, v0, v1
	v_lshl_add_u32 v136, v2, 7, v8
	v_ashrrev_i32_e32 v8, 10, v1
	v_mul_i32_i24_e32 v1, 0x400, v8
	v_sub_u32_e32 v0, v0, v1
	v_lshrrev_b32_e32 v1, 4, v0
	v_bitop3_b32 v0, v1, v0, 32 bitop3:0x6c
	v_ashrrev_i32_e32 v2, 31, v0
	v_lshrrev_b32_e32 v2, 26, v2
	v_add_u32_e32 v2, v0, v2
	v_ashrrev_i32_e32 v9, 6, v2
	v_and_b32_e32 v2, 0xffc0, v2
	v_sub_u32_e32 v0, v0, v2
	v_lshrrev_b16_e32 v2, 7, v0
	v_lshlrev_b32_e32 v1, 3, v8
	v_and_b32_e32 v2, 1, v2
	v_and_b32_e32 v1, -16, v1
	v_add_u16_e32 v0, v0, v2
	v_add_u32_e32 v1, v9, v1
	v_ashrrev_i16_sdwa v0, v3, sext(v0) dst_sel:DWORD dst_unused:UNUSED_PAD src0_sel:DWORD src1_sel:BYTE_0
	v_and_b32_e32 v3, 3, v9
	s_lshl_b32 s2, s2, 3
	v_and_or_b32 v3, v1, s3, v3
	s_and_b32 s2, s2, 56
	v_readlane_b32 s3, v254, 16
	s_add_i32 s2, s2, s3
	v_lshlrev_b32_e32 v10, 5, v8
	s_ashr_i32 s3, s2, 31
	v_and_b32_e32 v11, 32, v10
	v_bfe_i32 v10, v0, 0, 16
	v_lshlrev_b32_e32 v0, 1, v1
	v_lshrrev_b32_e32 v2, 2, v1
	s_lshl_b64 s[6:7], s[2:3], 22
	s_lshl_b32 s3, s82, 22
	v_and_b32_e32 v0, 24, v0
	v_and_b32_e32 v2, 4, v2
	s_add_u32 s4, s72, s3
	v_or3_b32 v0, v3, v2, v0
	v_add_lshl_u32 v2, v11, v10, 1
	s_addc_u32 s5, s73, 0
	v_lshl_add_u32 v142, v0, 14, v2
	global_load_lds_dwordx4 v138, s[4:5]
	s_mov_b32 m0, s84
	s_add_u32 s8, s4, 0x200000
	global_load_lds_dwordx4 v142, s[4:5]
	s_addc_u32 s9, s5, 0
	s_mov_b32 m0, s85
	v_readlane_b32 s10, v254, 20
	global_load_lds_dwordx4 v138, s[8:9]
	s_mov_b32 m0, s10
	s_add_u32 s24, s70, s6
	global_load_lds_dwordx4 v142, s[8:9]
	s_addc_u32 s25, s71, s7
	s_mov_b32 m0, s33
	v_lshl_add_u32 v140, v1, 7, v2
	global_load_lds_dwordx4 v136, s[24:25]
	s_mov_b32 m0, s88
	s_add_u32 s6, s24, 0x4000
	global_load_lds_dwordx4 v140, s[24:25]
	s_addc_u32 s7, s25, 0
	s_mov_b32 m0, s89
	v_mov_b32_e32 v139, 0
	global_load_lds_dwordx4 v136, s[6:7]
	s_mov_b32 m0, s90
	v_mov_b32_e32 v143, v139
	global_load_lds_dwordx4 v140, s[6:7]
	v_lshl_add_u64 v[2:3], s[4:5], 0, v[138:139]
	v_lshl_add_u64 v[0:1], s[4:5], 0, v[142:143]
	v_mov_b32_e32 v137, v139
	s_and_b64 vcc, exec, s[0:1]
	v_mov_b32_e32 v141, v139
	s_cbranch_vccnz .LBB0_670
	s_barrier
.LBB0_670:
	v_readlane_b32 s6, v254, 23
	s_mov_b32 m0, s6
	s_add_u32 s42, s66, 0x50000
	s_mov_b64 s[6:7], 0x80
	s_addc_u32 s43, s67, 0
	v_lshl_add_u64 v[2:3], v[2:3], 0, s[6:7]
	v_readlane_b32 s8, v254, 24
	s_waitcnt vmcnt(2)
	s_barrier
	global_load_lds_dwordx4 v[2:3], off
	s_mov_b32 m0, s8
	s_add_u32 s8, s24, 0x8000
	v_lshl_add_u64 v[0:1], v[0:1], 0, s[6:7]
	s_addc_u32 s9, s25, 0
	global_load_lds_dwordx4 v[0:1], off
	v_lshl_add_u64 v[0:1], s[8:9], 0, v[136:137]
	s_mov_b32 m0, s92
	v_readlane_b32 s10, v254, 25
	global_load_lds_dwordx4 v[0:1], off
	v_lshl_add_u64 v[0:1], s[8:9], 0, v[140:141]
	s_add_u32 s8, s4, 0x200080
	s_mov_b32 m0, s93
	s_addc_u32 s9, s5, 0
	global_load_lds_dwordx4 v[0:1], off
	v_lshl_add_u64 v[0:1], s[8:9], 0, v[138:139]
	s_mov_b32 m0, s10
	v_and_b32_e32 v172, 15, v7
	global_load_lds_dwordx4 v[0:1], off
	v_lshl_add_u64 v[0:1], s[8:9], 0, v[142:143]
	v_readlane_b32 s8, v254, 26
	s_mov_b32 m0, s8
	v_and_b32_e32 v3, 48, v7
	global_load_lds_dwordx4 v[0:1], off
	v_or_b32_e32 v0, s77, v172
	v_ashrrev_i32_e32 v1, 6, v7
	v_lshlrev_b32_e32 v2, 6, v0
	s_movk_i32 s8, 0x3c0
	v_lshlrev_b32_e32 v0, 2, v0
	v_and_or_b32 v2, v2, s8, v3
	v_and_b32_e32 v0, 32, v0
	v_lshl_add_u32 v11, v1, 10, s83
	v_ashrrev_i32_e32 v173, 4, v7
	v_lshlrev_b32_e32 v7, 2, v7
	v_bitop3_b32 v0, v2, v11, v0 bitop3:0xde
	s_add_i32 s8, s2, 4
	s_lshl_b32 s9, s82, 8
	v_lshlrev_b32_e32 v2, 10, v4
	v_lshl_or_b32 v3, v172, 6, v3
	v_and_b32_e32 v7, 32, v7
	v_add_lshl_u32 v1, v1, s75, 10
	s_or_b32 s44, s9, s74
	s_ashr_i32 s9, s8, 31
	v_and_b32_e32 v2, 0xfffff800, v2
	v_bitop3_b32 v1, v3, v1, v7 bitop3:0xde
	s_lshl_b64 s[10:11], s[8:9], 22
	v_lshl_add_u32 v2, v5, 7, v2
	v_and_b32_e32 v3, 1, v4
	s_add_u32 s10, s70, s10
	v_lshl_or_b32 v2, v3, 6, v2
	s_addc_u32 s11, s71, s11
	v_lshl_add_u32 v144, v6, 1, v2
	v_lshlrev_b32_e32 v2, 10, v8
	s_add_u32 s3, s66, s3
	v_and_b32_e32 v2, 0xfffff800, v2
	s_waitcnt vmcnt(6)
	s_addc_u32 s9, s67, 0
	v_lshl_add_u32 v2, v9, 7, v2
	v_and_b32_e32 v3, 1, v8
	s_add_u32 s20, s3, 0x3600100
	v_lshl_or_b32 v2, v3, 6, v2
	s_addc_u32 s21, s9, 0
	v_mov_b32_e32 v145, v139
	v_lshl_add_u32 v146, v10, 1, v2
	v_mov_b32_e32 v147, v139
	s_mov_b64 s[22:23], -1
	v_add_u32_e32 v174, s31, v1
	v_add_u32_e32 v175, s30, v1
	v_add_u32_e32 v176, 0, v0
	v_mov_b32_e32 v177, 0x358637bd
	s_mov_b32 s9, 0xf800000
	v_mov_b32_e32 v178, 0x260
	v_add_u32_e32 v179, s29, v1
	v_add_u32_e32 v180, s41, v1
	s_barrier
	s_branch .LBB0_673

	.amdhsa_kernel _Z14fwd_megakernel4Args
		.amdhsa_group_segment_fixed_size 0
		.amdhsa_private_segment_fixed_size 0
		.amdhsa_kernarg_size 368
		.amdhsa_user_sgpr_count 2
		.amdhsa_user_sgpr_dispatch_ptr 0
		.amdhsa_user_sgpr_queue_ptr 0
		.amdhsa_user_sgpr_kernarg_segment_ptr 1
		.amdhsa_user_sgpr_dispatch_id 0
		.amdhsa_user_sgpr_kernarg_preload_length 0
		.amdhsa_user_sgpr_kernarg_preload_offset 0
		.amdhsa_user_sgpr_private_segment_size 0
		.amdhsa_uses_dynamic_stack 0
		.amdhsa_enable_private_segment 0
		.amdhsa_system_sgpr_workgroup_id_x 1
		.amdhsa_system_sgpr_workgroup_id_y 0
		.amdhsa_system_sgpr_workgroup_id_z 0
		.amdhsa_system_sgpr_workgroup_info 0
		.amdhsa_system_vgpr_workitem_id 2
		.amdhsa_next_free_vgpr 256
		.amdhsa_next_free_sgpr 102
		.amdhsa_accum_offset 256
		.amdhsa_reserve_vcc 1
		.amdhsa_float_round_mode_32 0
		.amdhsa_float_round_mode_16_64 0
		.amdhsa_float_denorm_mode_32 3
		.amdhsa_float_denorm_mode_16_64 3
		.amdhsa_dx10_clamp 1
		.amdhsa_ieee_mode 1
		.amdhsa_fp16_overflow 0
		.amdhsa_tg_split 0
		.amdhsa_exception_fp_ieee_invalid_op 0
		.amdhsa_exception_fp_denorm_src 0
		.amdhsa_exception_fp_ieee_div_zero 0
		.amdhsa_exception_fp_ieee_overflow 0
		.amdhsa_exception_fp_ieee_underflow 0
		.amdhsa_exception_fp_ieee_inexact 0
		.amdhsa_exception_int_div_zero 0
	.end_amdhsa_kernel

amdhsa.kernels:
  - .agpr_count:     0
    .args:
      - .offset:         0
        .size:           112
        .value_kind:     by_value
      - .offset:         112
        .size:           4
        .value_kind:     hidden_block_count_x
      - .offset:         116
        .size:           4
        .value_kind:     hidden_block_count_y
      - .offset:         120
        .size:           4
        .value_kind:     hidden_block_count_z
      - .offset:         124
        .size:           2
        .value_kind:     hidden_group_size_x
      - .offset:         126
        .size:           2
        .value_kind:     hidden_group_size_y
      - .offset:         128
        .size:           2
        .value_kind:     hidden_group_size_z
      - .offset:         130
        .size:           2
        .value_kind:     hidden_remainder_x
      - .offset:         132
        .size:           2
        .value_kind:     hidden_remainder_y
      - .offset:         134
        .size:           2
        .value_kind:     hidden_remainder_z
      - .offset:         152
        .size:           8
        .value_kind:     hidden_global_offset_x
      - .offset:         160
        .size:           8
        .value_kind:     hidden_global_offset_y
      - .offset:         168
        .size:           8
        .value_kind:     hidden_global_offset_z
      - .offset:         176
        .size:           2
        .value_kind:     hidden_grid_dims
      - .offset:         200
        .size:           8
        .value_kind:     hidden_multigrid_sync_arg
      - .offset:         232
        .size:           4
        .value_kind:     hidden_dynamic_lds_size
    .group_segment_fixed_size: 0
    .kernarg_segment_align: 8
    .kernarg_segment_size: 368
    .language:       OpenCL C
    .language_version:
      - 2
      - 0
    .max_flat_workgroup_size: 512
    .name:           _Z14fwd_megakernel4Args
    .private_segment_fixed_size: 0
    .sgpr_count:     108
    .sgpr_spill_count: 38
    .symbol:         _Z14fwd_megakernel4Args.kd
    .uniform_work_group_size: 1
    .uses_dynamic_stack: false
    .vgpr_count:     256
    .vgpr_spill_count: 0
    .wavefront_size: 64
